# 4-unit dilated-first workgroups skip the seam memory-attention unit (those units run from the P2 queue instead)
# baseline (speedup 1.0000x reference)
; #define LAS __attribute__((address_space(3)))
; DI int q_next(gu32* ctr, volatile LAS int* slot, int tid) {
;     __syncthreads();
;     if (tid == 0) *slot = (int)__hip_atomic_fetch_add(ctr, 1u, RLX_AGENT);
;     __syncthreads();
;     return *slot;
; __global__ void __launch_bounds__(NT, 2) fwd(Args args) {
;     ...
;         if (!sfirst) {
;             volatile LAS int* slot = (volatile LAS int*)(MISC + 16);
;             int u = __builtin_amdgcn_readfirstlane(q_next(ctl + CW_Q0 + (pass * 8 + 4) * 64, slot, tid));
;             if (u < 256) unit_memattn(u, MQB, MKB, MVB, GB, MIX, CB, UB, args.in[10], lds, tid, lane, wave);
;             else { u = __builtin_amdgcn_readfirstlane(q_next(ctl + CW_Q0 + (pass * 8 + 6) * 64, slot, tid));
;                 if (u < 256) unit_sample_mem(u, MQB, args.in[6], args.in[7], GB, MIX, CB, UB, args.in[5], args.in[10], lds, tid, lane, wave); }
;             early_wait((unsigned*)(ctl + CW_EB), bar.bar, bar.st); } }
.LBB0_616:
	s_or_b64 exec, exec, s[0:1]
	s_xor_b64 s[0:1], s[34:35], -1
	s_andn2_b64 vcc, exec, s[0:1]
	s_barrier
	s_cbranch_vccnz .LBB0_696
	s_cmpk_lt_u32 s96, 0xa0
	s_cbranch_scc1 .Lskip_seam
	v_readlane_b32 s0, v247, 41
	v_readlane_b32 s2, v247, 43
	v_readlane_b32 s1, v247, 42
	s_lshl_b32 s0, s2, 9
	s_ashr_i32 s1, s0, 31
	s_lshl_b64 s[0:1], s[0:1], 2
	s_add_u32 s0, s82, s0
	s_addc_u32 s1, s83, s1
	s_add_u32 s0, s0, 0x6e00
	v_readlane_b32 s3, v247, 44
	s_addc_u32 s1, s1, 0
	s_barrier
	s_and_saveexec_b64 s[2:3], s[56:57]
	s_cbranch_execz .LBB0_621
	s_mov_b64 s[10:11], exec
	v_mbcnt_lo_u32_b32 v1, s10, 0
	v_mbcnt_hi_u32_b32 v1, s11, v1
	v_cmp_eq_u32_e32 vcc, 0, v1
	s_and_saveexec_b64 s[8:9], vcc
	s_cbranch_execz .LBB0_620
	s_bcnt1_i32_b64 s10, s[10:11]
	v_mov_b32_e32 v2, 0
	v_mov_b32_e32 v3, s10
	global_atomic_add v2, v2, v3, s[0:1] offset:1024 sc0

; #define LAS __attribute__((address_space(3)))
; DI v2u pack4(f32x4 a) { v2u w; w.x = cvtpk(a[0], a[1]); w.y = cvtpk(a[2], a[3]); return w; }
; DI void unit_memattn(int u, const bf16* __restrict__ MQ, const bf16* __restrict__ MK, const bf16* __restrict__ MV, const bf16* __restrict__ G, bf16* __restrict__ MIX, const bf16* __restrict__ CB, const bf16* __restrict__ U, const float* __restrict__ convw, ...
;     ...
;         const float inv = 1.f / l; const int rl = 32 * wave + qq, sw = (rl ^ (rl >> 3) ^ (rl >> 6)) & 7;
;         LAS unsigned char* ob = lds + 94208 + rl * 128 + 8 * hh;
; #pragma unroll
;         for (int g = 0; g < 4; ++g) {
;             *(LAS v2u*)(ob + ((g ^ sw) << 4)) = pack4((f32x4){o0[4 * g], o0[4 * g + 1], o0[4 * g + 2], o0[4 * g + 3]} * inv);
;             *(LAS v2u*)(ob + (((4 + g) ^ sw) << 4)) = pack4((f32x4){o1[4 * g], o1[4 * g + 1], o1[4 * g + 2], o1[4 * g + 3]} * inv); }
;     }
;     __syncthreads();
;     {   v4u ov[4];
; #pragma unroll
;         for (int i = 0; i < 4; ++i) { const int id = tid + NT * i, rl = id >> 3, c = id & 7;
;             ov[i] = *(LAS const v4u*)(lds + 94208 + rl * 128 + ((c ^ ((rl ^ (rl >> 3) ^ (rl >> 6)) & 7)) << 4)); }
.LBB0_680:
	v_div_scale_f32 v34, s[2:3], v151, v151, 1.0
	v_rcp_f32_e32 v35, v34
	v_div_scale_f32 v36, vcc, 1.0, v151, 1.0
	s_movk_i32 s2, 0x50
	v_fma_f32 v37, -v34, v35, 1.0
	v_fmac_f32_e32 v35, v37, v35
	v_mul_f32_e32 v37, v36, v35
	v_fma_f32 v38, -v34, v37, v36
	v_fmac_f32_e32 v37, v38, v35
	v_fma_f32 v34, -v34, v37, v36
	v_div_fmas_f32 v34, v34, v35, v37
	v_or_b32_e32 v35, s0, v131
	v_lshrrev_b32_e32 v36, 3, v35
	s_lshr_b32 s0, s84, 7
	v_xor_b32_e32 v36, s0, v36
	v_lshlrev_b32_e32 v35, 7, v35
	s_add_i32 s0, 0, 0x17000
	v_div_fixup_f32 v34, v34, v151, 1.0
	v_add3_u32 v35, s0, v35, v148
	v_xor_b32_e32 v36, v36, v150
	v_pk_mul_f32 v[4:5], v[34:35], v[4:5] op_sel_hi:[0,1]
	v_pk_mul_f32 v[2:3], v[34:35], v[2:3] op_sel_hi:[0,1]
	v_cvt_pk_bf16_f32 v2, v2, v3
	v_cvt_pk_bf16_f32 v3, v4, v5
	v_lshlrev_b32_e32 v4, 4, v36
	v_and_b32_e32 v36, 0x70, v4
	v_add_u32_e32 v4, v35, v36
	ds_write_b64 v4, v[2:3]
	v_pk_mul_f32 v[2:3], v[34:35], v[20:21] op_sel_hi:[0,1]
	v_pk_mul_f32 v[4:5], v[34:35], v[18:19] op_sel_hi:[0,1]
	v_cvt_pk_bf16_f32 v4, v4, v5
	v_cvt_pk_bf16_f32 v5, v2, v3
	v_xad_u32 v2, v36, 64, v35
	ds_write_b64 v2, v[4:5]
	v_pk_mul_f32 v[2:3], v[34:35], v[8:9] op_sel_hi:[0,1]
	v_pk_mul_f32 v[4:5], v[34:35], v[6:7] op_sel_hi:[0,1]
	v_cvt_pk_bf16_f32 v4, v4, v5
	v_cvt_pk_bf16_f32 v5, v2, v3
	v_xad_u32 v2, v36, 16, v35
	ds_write_b64 v2, v[4:5]
	v_pk_mul_f32 v[2:3], v[34:35], v[24:25] op_sel_hi:[0,1]
	v_pk_mul_f32 v[4:5], v[34:35], v[22:23] op_sel_hi:[0,1]
	v_cvt_pk_bf16_f32 v4, v4, v5
	v_cvt_pk_bf16_f32 v5, v2, v3
	v_xad_u32 v2, v36, s2, v35
	ds_write_b64 v2, v[4:5]
	v_pk_mul_f32 v[2:3], v[34:35], v[12:13] op_sel_hi:[0,1]
	v_pk_mul_f32 v[4:5], v[34:35], v[10:11] op_sel_hi:[0,1]
	v_cvt_pk_bf16_f32 v4, v4, v5
	v_cvt_pk_bf16_f32 v5, v2, v3
	v_xad_u32 v2, v36, 32, v35
	ds_write_b64 v2, v[4:5]
	v_pk_mul_f32 v[2:3], v[34:35], v[28:29] op_sel_hi:[0,1]
	v_pk_mul_f32 v[4:5], v[34:35], v[26:27] op_sel_hi:[0,1]
	s_movk_i32 s2, 0x60
	v_cvt_pk_bf16_f32 v4, v4, v5
	v_cvt_pk_bf16_f32 v5, v2, v3
	v_xad_u32 v2, v36, s2, v35
	ds_write_b64 v2, v[4:5]
	v_pk_mul_f32 v[2:3], v[34:35], v[16:17] op_sel_hi:[0,1]
	v_pk_mul_f32 v[4:5], v[34:35], v[14:15] op_sel_hi:[0,1]
	v_cvt_pk_bf16_f32 v4, v4, v5
	v_cvt_pk_bf16_f32 v5, v2, v3
	v_xad_u32 v2, v36, 48, v35
	s_movk_i32 s1, 0x70
	ds_write_b64 v2, v[4:5]
	v_pk_mul_f32 v[2:3], v[34:35], v[32:33] op_sel_hi:[0,1]
	v_pk_mul_f32 v[4:5], v[34:35], v[30:31] op_sel_hi:[0,1]
	v_cvt_pk_bf16_f32 v4, v4, v5
	v_cvt_pk_bf16_f32 v5, v2, v3
	v_xad_u32 v2, v36, s1, v35
	v_lshrrev_b32_e32 v3, 9, v1
	ds_write_b64 v2, v[4:5]
	v_lshrrev_b32_e32 v10, 6, v1
	v_xor_b32_e32 v3, v1, v3
	v_lshrrev_b32_e32 v4, 9, v141
	v_xor_b32_e32 v3, v3, v10
	v_xor_b32_e32 v4, v1, v4
	v_xor_b32_e32 v3, v3, v140
	v_xor_b32_e32 v4, v4, v10
	v_lshlrev_b32_e32 v3, 4, v3
	v_xor_b32_e32 v4, v4, v142
	v_lshlrev_b32_e32 v2, 7, v140
	v_and_b32_e32 v3, 0x70, v3
	v_lshlrev_b32_e32 v4, 4, v4
	v_add3_u32 v2, s0, v2, v3
	v_lshlrev_b32_e32 v3, 7, v142
	v_and_b32_e32 v4, 0x70, v4
	v_add3_u32 v6, s0, v3, v4
	s_waitcnt lgkmcnt(0)
	s_barrier
; #define LAS __attribute__((address_space(3)))
; DI unsigned cvtpk(float lo, float hi) { f32x2_t v = {lo, hi}; bf16x2_t b = __builtin_convertvector(v, bf16x2_t); return __builtin_bit_cast(unsigned, b); }
; DI void unit_memattn(int u, const bf16* __restrict__ MQ, const bf16* __restrict__ MK, const bf16* __restrict__ MV, const bf16* __restrict__ G, bf16* __restrict__ MIX, const bf16* __restrict__ CB, const bf16* __restrict__ U, const float* __restrict__ convw, ...
;     ...
;     {   v4u ov[4];
; #pragma unroll
;         for (int i = 0; i < 4; ++i) { const int id = tid + NT * i, rl = id >> 3, c = id & 7;
;             ov[i] = *(LAS const v4u*)(lds + 94208 + rl * 128 + ((c ^ ((rl ^ (rl >> 3) ^ (rl >> 6)) & 7)) << 4)); }
; #pragma unroll
;         for (int i = 0; i < 4; ++i) { const int id = tid + NT * i, rl = id >> 3, c = id & 7; v4u w;
; #pragma unroll
;             for (int e = 0; e < 4; ++e) w[e] = cvtpk(bflo(ov[i][e]) * bflo(gv[i][e]), bfhi(ov[i][e]) * bfhi(gv[i][e]));
;             *(v4u*)(MIX + ((size_t)b * SEQ + qb * 256 + rl) * D + 768 + hm * 64 + c * 8) = w; }
;     }
; __global__ void __launch_bounds__(NT, 2) fwd(Args args) {
;     ...
;             early_wait((unsigned*)(ctl + CW_EB), bar.bar, bar.st); } }
	ds_read_b128 v[2:5], v2
	ds_read_b128 v[6:9], v6
	v_lshlrev_b32_e32 v20, 16, v78
	v_and_b32_e32 v21, 0xffff0000, v78
	v_lshrrev_b32_e32 v12, 9, v143
	s_waitcnt lgkmcnt(1)
	v_lshlrev_b32_e32 v18, 16, v2
	v_and_b32_e32 v19, 0xffff0000, v2
	v_pk_mul_f32 v[18:19], v[20:21], v[18:19]
	v_lshlrev_b32_e32 v20, 16, v79
	v_cvt_pk_bf16_f32 v2, v18, v19
	v_lshlrev_b32_e32 v18, 16, v3
	v_and_b32_e32 v19, 0xffff0000, v3
	v_and_b32_e32 v21, 0xffff0000, v79
	v_pk_mul_f32 v[18:19], v[20:21], v[18:19]
	v_lshlrev_b32_e32 v20, 16, v80
	v_cvt_pk_bf16_f32 v3, v18, v19
	v_lshlrev_b32_e32 v18, 16, v4
	v_and_b32_e32 v19, 0xffff0000, v4
	v_and_b32_e32 v21, 0xffff0000, v80
	v_xor_b32_e32 v12, v1, v12
	v_lshrrev_b32_e32 v13, 9, v145
	v_pk_mul_f32 v[18:19], v[20:21], v[18:19]
	v_xor_b32_e32 v12, v12, v10
	v_xor_b32_e32 v1, v1, v13
	v_cvt_pk_bf16_f32 v4, v18, v19
	v_lshlrev_b32_e32 v18, 16, v5
	v_and_b32_e32 v19, 0xffff0000, v5
	v_lshlrev_b32_e32 v20, 16, v81
	v_and_b32_e32 v21, 0xffff0000, v81
	v_xor_b32_e32 v12, v12, v144
	v_xor_b32_e32 v1, v1, v10
	v_pk_mul_f32 v[18:19], v[20:21], v[18:19]
	s_mov_b32 s9, 0
	v_lshlrev_b32_e32 v12, 4, v12
	v_xor_b32_e32 v1, v1, v146
	v_cvt_pk_bf16_f32 v5, v18, v19
	v_lshl_add_u64 v[18:19], s[36:37], 0, v[138:139]
	v_lshlrev_b32_e32 v11, 7, v144
	v_and_b32_e32 v12, 0x70, v12
	v_lshlrev_b32_e32 v1, 4, v1
	v_lshl_add_u64 v[18:19], v[18:19], 0, s[8:9]
	v_mov_b32_e32 v131, 0
	v_add3_u32 v11, s0, v11, v12
	v_lshlrev_b32_e32 v12, 7, v146
	v_and_b32_e32 v1, 0x70, v1
	v_lshl_add_u64 v[18:19], v[18:19], 0, v[130:131]
	v_add3_u32 v1, s0, v12, v1
	ds_read_b128 v[10:13], v11
	ds_read_b128 v[14:17], v1
	global_store_dwordx4 v[18:19], v[2:5], off offset:1536
	s_waitcnt lgkmcnt(2)
	s_nop 0
	v_lshlrev_b32_e32 v2, 16, v6
	v_and_b32_e32 v3, 0xffff0000, v6
	v_lshlrev_b32_e32 v4, 16, v74
	v_and_b32_e32 v5, 0xffff0000, v74
	v_pk_mul_f32 v[2:3], v[4:5], v[2:3]
	v_lshlrev_b32_e32 v4, 16, v7
	v_and_b32_e32 v5, 0xffff0000, v7
	v_lshlrev_b32_e32 v6, 16, v75
	v_and_b32_e32 v7, 0xffff0000, v75
	v_pk_mul_f32 v[4:5], v[6:7], v[4:5]
	v_cvt_pk_bf16_f32 v2, v2, v3
	v_cvt_pk_bf16_f32 v3, v4, v5
	v_lshlrev_b32_e32 v4, 16, v8
	v_and_b32_e32 v5, 0xffff0000, v8
	v_lshlrev_b32_e32 v6, 16, v76
	v_and_b32_e32 v7, 0xffff0000, v76
	v_pk_mul_f32 v[4:5], v[6:7], v[4:5]
	v_lshlrev_b32_e32 v6, 16, v9
	v_and_b32_e32 v7, 0xffff0000, v9
	v_lshlrev_b32_e32 v8, 16, v77
	v_and_b32_e32 v9, 0xffff0000, v77
	v_pk_mul_f32 v[6:7], v[8:9], v[6:7]
	v_cvt_pk_bf16_f32 v4, v4, v5
	v_cvt_pk_bf16_f32 v5, v6, v7
	v_lshl_add_u64 v[6:7], s[36:37], 0, v[136:137]
	v_lshl_add_u64 v[6:7], v[6:7], 0, s[8:9]
	v_lshl_add_u64 v[6:7], v[6:7], 0, v[130:131]
	global_store_dwordx4 v[6:7], v[2:5], off offset:1536
	v_lshlrev_b32_e32 v6, 16, v71
	v_and_b32_e32 v7, 0xffff0000, v71
	s_waitcnt lgkmcnt(1)
	v_lshlrev_b32_e32 v2, 16, v10
	v_and_b32_e32 v3, 0xffff0000, v10
	v_lshlrev_b32_e32 v4, 16, v70
	v_and_b32_e32 v5, 0xffff0000, v70
	v_pk_mul_f32 v[2:3], v[4:5], v[2:3]
	v_lshlrev_b32_e32 v4, 16, v11
	v_and_b32_e32 v5, 0xffff0000, v11
	v_pk_mul_f32 v[4:5], v[6:7], v[4:5]
	v_cvt_pk_bf16_f32 v2, v2, v3
	v_cvt_pk_bf16_f32 v3, v4, v5
	v_lshlrev_b32_e32 v4, 16, v12
	v_and_b32_e32 v5, 0xffff0000, v12
	v_lshlrev_b32_e32 v6, 16, v72
	v_and_b32_e32 v7, 0xffff0000, v72
	v_pk_mul_f32 v[4:5], v[6:7], v[4:5]
	v_lshlrev_b32_e32 v6, 16, v13
	v_and_b32_e32 v7, 0xffff0000, v13
	v_lshlrev_b32_e32 v8, 16, v73
	v_and_b32_e32 v9, 0xffff0000, v73
	v_pk_mul_f32 v[6:7], v[8:9], v[6:7]
	v_cvt_pk_bf16_f32 v4, v4, v5
	v_cvt_pk_bf16_f32 v5, v6, v7
	v_lshl_add_u64 v[6:7], s[36:37], 0, v[134:135]
	v_lshl_add_u64 v[6:7], v[6:7], 0, s[8:9]
	v_lshl_add_u64 v[6:7], v[6:7], 0, v[130:131]
	global_store_dwordx4 v[6:7], v[2:5], off offset:1536
	v_lshlrev_b32_e32 v6, 16, v67
	v_and_b32_e32 v7, 0xffff0000, v67
	s_waitcnt lgkmcnt(0)
	v_lshlrev_b32_e32 v2, 16, v14
	v_and_b32_e32 v3, 0xffff0000, v14
	v_lshlrev_b32_e32 v4, 16, v66
	v_and_b32_e32 v5, 0xffff0000, v66
	v_pk_mul_f32 v[2:3], v[4:5], v[2:3]
	v_lshlrev_b32_e32 v4, 16, v15
	v_and_b32_e32 v5, 0xffff0000, v15
	v_pk_mul_f32 v[4:5], v[6:7], v[4:5]
	v_cvt_pk_bf16_f32 v2, v2, v3
	v_cvt_pk_bf16_f32 v3, v4, v5
	v_lshlrev_b32_e32 v4, 16, v16
	v_and_b32_e32 v5, 0xffff0000, v16
	v_lshlrev_b32_e32 v6, 16, v68
	v_and_b32_e32 v7, 0xffff0000, v68
	v_pk_mul_f32 v[4:5], v[6:7], v[4:5]
	v_lshlrev_b32_e32 v6, 16, v17
	v_and_b32_e32 v7, 0xffff0000, v17
	v_lshlrev_b32_e32 v8, 16, v69
	v_and_b32_e32 v9, 0xffff0000, v69
	v_pk_mul_f32 v[6:7], v[8:9], v[6:7]
	v_cvt_pk_bf16_f32 v4, v4, v5
	v_cvt_pk_bf16_f32 v5, v6, v7
	v_lshl_add_u64 v[6:7], s[36:37], 0, v[132:133]
	v_lshl_add_u64 v[6:7], v[6:7], 0, s[8:9]
	v_lshl_add_u64 v[6:7], v[6:7], 0, v[130:131]
	global_store_dwordx4 v[6:7], v[2:5], off offset:1536
	s_and_saveexec_b64 s[0:1], s[56:57]
	s_cbranch_execz .LBB0_695
.Lskip_seam_never:
	s_branch .LBB0_681
.Lskip_seam:
	s_and_saveexec_b64 s[0:1], s[56:57]
	s_cbranch_execz .LBB0_695
